# P0 role specialisation: waves 0-3 convert all weight items, waves 4-7 run all RMSNorm rows concurrently; nt once-read loads
# baseline (speedup 1.0000x reference)
; #define KARG ((const __attribute__((address_space(4))) Args*)__builtin_amdgcn_kernarg_segment_ptr())
; #define STAMP(i) do { if (F.bid == PROBE_BID && F.tid == 0 && ((i) == PROBE_A || (i) == PROBE_B)) { const unsigned long long t_ = __builtin_amdgcn_s_memrealtime(); volatile LAS unsigned* m_ = (volatile LAS unsigned*)(F.lds + MISC_OFF) + ((i) == PROBE_A ? 16 : 18); m_[0] = (unsigned)t_; m_[1] = (unsigned)(t_ >> 32); } } while (0)
; #define STAMP(i) do { } while (0)
; #define SEAM(k) do { if (IN(k) && IN((k) + 1)) { XcdBarrier b_; b_.bar = (unsigned*)(P_ctl + CW_BAR); b_.x = xb_xcc_id(); b_.st = MISC + 8; xcd_barrier(b_); } } while (0)
; __device__ __forceinline__ void p0_prologue(const Frame& F, const Ptrs& P) {
;     const int gw = F.bid * NWAVES + F.wave, NGW = F.G * NWAVES;
;     convert_weights<0>(F, gw, NGW);
;     for (int m = gw; m < M; m += NGW) { const float* xr = (m < MP) ? P_x_prompt + (size_t)m * DM : P_x_sample + (size_t)(m - MP) * DM; rms_row_to_bf16(xr, P_mix_nw, P_XN + (size_t)m * DM, F.lane); }
; __global__ void __launch_bounds__(NWAVES * 64, 2) hymba_fwd(Args args) {
;     ...
;     const int lo = KARG->ph_lo, hi = KARG->ph_hi;
;     STAMP(0);
;     ...
;     if (IN(0)) { for (int rep = 0; rep < NREP_P0; ++rep) p0_prologue(F, P); } SEAM(0); STAMP(1);
.LBB0_5:
	s_or_b64 exec, exec, s[4:5]
	s_load_dwordx2 s[6:7], s[0:1], 0xe0
	s_lshr_b32 s94, s60, 6
	v_and_b32_e32 v189, 63, v0
	s_waitcnt lgkmcnt(0)
	s_cmp_lt_i32 s6, 1
	s_cselect_b64 s[4:5], -1, 0
	s_cmp_gt_i32 s7, 0
	s_cselect_b64 s[6:7], -1, 0
	s_and_b64 s[6:7], s[4:5], s[6:7]
	s_andn2_b64 vcc, exec, s[6:7]
	s_cbranch_vccnz .LBB0_20
	s_cmp_lt_u32 s94, 4
	s_cbranch_scc0 .Lp0_rms_role
	s_mul_i32 s4, s2, 4
	s_add_i32 s8, s94, s4
	s_mul_i32 s10, s3, 4
	s_cmpk_gt_i32 s8, 0x683f
	s_cbranch_scc1 .LBB0_20
	s_branch .Lp0_conv_role
.Lp0_rms_role:
	s_mov_b32 s98, 1
	s_mul_i32 s4, s2, 4
	s_sub_i32 s8, s94, 4
	s_add_i32 s8, s8, s4
	s_mul_i32 s10, s3, 4
	s_branch .LBB0_13
.Lp0_conv_role:
	s_lshl_b32 s4, s94, 14
	s_add_i32 s9, s4, 0
	v_lshrrev_b32_e32 v1, 5, v189
	v_and_b32_e32 v14, 31, v0
	v_and_b32_e32 v2, 7, v0
	v_lshrrev_b32_e32 v7, 3, v189
	v_mov_b32_e32 v3, 0
	v_lshl_add_u32 v12, v14, 2, s9
	v_mul_u32_u24_e32 v13, 0x84, v1
	v_lshlrev_b32_e32 v6, 3, v2
	v_mul_u32_u24_e32 v4, 0x420, v2
	v_lshlrev_b32_e32 v5, 2, v7
	v_lshlrev_b32_e32 v2, 4, v2
	s_add_u32 s4, s50, 0x19600000
	v_add3_u32 v8, s9, v4, v5
	v_lshl_add_u64 v[4:5], s[50:51], 0, v[2:3]
	s_mov_b64 s[12:13], 0x14c00000
	v_add_u32_e32 v12, v12, v13
	s_addc_u32 s5, s51, 0
	v_or_b32_e32 v9, 8, v7
	v_or_b32_e32 v10, 16, v7
	v_or_b32_e32 v11, 24, v7
	v_lshl_add_u64 v[4:5], v[4:5], 0, s[12:13]
	s_lshl_b32 s9, s8, 5
	s_lshl_b32 s11, s10, 5
	s_mov_b32 s16, 0x8000
	s_mov_b32 s17, 0x10000
	s_mov_b32 s18, 0x18000
	s_mov_b32 s19, 0x20000
	s_mov_b32 s20, 0x28000
	s_mov_b32 s21, 0x30000
	s_mov_b32 s22, 0x38000
	s_mov_b32 s23, 0x40000
	s_mov_b32 s24, 0x48000
	s_mov_b32 s25, 0x50000
	s_mov_b32 s26, 0x58000
	s_mov_b32 s27, 0x60000
	s_mov_b32 s28, 0x68000
	s_mov_b32 s29, 0x70000
	s_mov_b32 s30, 0x78000
	s_mov_b32 s31, 0x80000
	s_mov_b32 s33, 0x88000
	s_mov_b32 s34, 0x90000
	s_mov_b32 s35, 0x98000
	s_mov_b32 s36, 0xa0000
	s_mov_b32 s37, 0xa8000
	s_mov_b32 s38, 0xb0000
	s_mov_b32 s39, 0xb8000
	s_mov_b32 s40, 0xc0000
	s_mov_b32 s41, 0xc8000
	s_mov_b32 s42, 0xd0000
	s_mov_b32 s43, 0xd8000
	s_mov_b32 s44, 0xe0000
	s_mov_b32 s45, 0xe8000
	s_mov_b32 s46, 0xf0000
	s_mov_b32 s47, 0xf8000
	s_mov_b32 s52, 0x9080
	v_lshlrev_b32_e32 v2, 2, v14
	v_add_u32_e32 v13, 0x400, v12
	v_add_u32_e32 v14, 0x800, v12
	v_add_u32_e32 v15, 0xc00, v12
	v_add_u32_e32 v16, 0x1000, v12
	v_add_u32_e32 v17, 0x1400, v12
	v_add_u32_e32 v18, 0x1800, v12
	v_add_u32_e32 v19, 0x1c00, v12
	v_mov_b32_e32 v20, 0x800
	s_mov_b32 s53, s8
	s_branch .LBB0_9

; __device__ __forceinline__ void rms_row_to_bf16(const float* xrow, const float* w, bf16* orow, int lane) {
;     const f32x4* xr = (const f32x4*)xrow + 2 * lane; f32x4 v[16];
; #pragma unroll
;     for (int j = 0; j < 8; ++j) { v[2 * j] = xr[128 * j]; v[2 * j + 1] = xr[128 * j + 1]; }
;     rms_regs_to_bf16(v, w, orow, lane);
; __device__ __forceinline__ void p0_prologue(const Frame& F, const Ptrs& P) {
;     const int gw = F.bid * NWAVES + F.wave, NGW = F.G * NWAVES;
;     convert_weights<0>(F, gw, NGW);
;     for (int m = gw; m < M; m += NGW) { const float* xr = (m < MP) ? P_x_prompt + (size_t)m * DM : P_x_sample + (size_t)(m - MP) * DM; rms_row_to_bf16(xr, P_mix_nw, P_XN + (size_t)m * DM, F.lane); }
.LBB0_13:
	s_cmp_eq_u32 s98, 0
	s_cbranch_scc1 .LBB0_20
	s_cmpk_gt_i32 s8, 0x23ff
	s_cbranch_scc1 .LBB0_20
	v_mbcnt_lo_u32_b32 v1, -1, 0
	v_mov_b32_e32 v67, 0
	v_lshlrev_b32_e32 v66, 4, v189
	v_mbcnt_hi_u32_b32 v3, -1, v1
	v_lshl_add_u64 v[4:5], s[50:51], 0, v[66:67]
	s_mov_b64 s[4:5], 0x10400000
	v_and_b32_e32 v1, 64, v3
	v_lshl_add_u64 v[68:69], v[4:5], 0, s[4:5]
	v_add_u32_e32 v4, 64, v1
	v_xor_b32_e32 v1, 1, v3
	v_cmp_lt_i32_e32 vcc, v1, v4
	v_xor_b32_e32 v5, 2, v3
	s_load_dwordx2 s[4:5], s[0:1], 0x40
	v_cndmask_b32_e32 v1, v3, v1, vcc
	v_cmp_lt_i32_e32 vcc, v5, v4
	v_lshlrev_b32_e32 v66, 5, v189
	v_lshlrev_b32_e32 v2, 1, v189
	v_cndmask_b32_e32 v5, v3, v5, vcc
	v_lshlrev_b32_e32 v85, 2, v5
	v_xor_b32_e32 v5, 4, v3
	v_cmp_lt_i32_e32 vcc, v5, v4
	s_waitcnt lgkmcnt(0)
	v_lshl_add_u64 v[70:71], s[4:5], 0, v[66:67]
	s_mov_b64 s[14:15], 0x1000
	v_cndmask_b32_e32 v5, v3, v5, vcc
	v_lshlrev_b32_e32 v86, 2, v5
	v_xor_b32_e32 v5, 8, v3
	v_cmp_lt_i32_e32 vcc, v5, v4
	s_mov_b64 s[16:17], 0x1800
	s_mov_b64 s[18:19], 0x2000
	v_cndmask_b32_e32 v5, v3, v5, vcc
	v_lshlrev_b32_e32 v87, 2, v5
	v_xor_b32_e32 v5, 16, v3
	v_cmp_lt_i32_e32 vcc, v5, v4
	s_mov_b64 s[20:21], 0x2800
	s_mov_b64 s[22:23], 0x3000
	v_cndmask_b32_e32 v5, v3, v5, vcc
	v_lshlrev_b32_e32 v88, 2, v5
	v_xor_b32_e32 v5, 32, v3
	v_cmp_lt_i32_e32 vcc, v5, v4
	s_mov_b64 s[24:25], 0x3800
	s_ashr_i32 s9, s8, 31
	v_cndmask_b32_e32 v3, v3, v5, vcc
	s_ashr_i32 s11, s10, 31
	s_mov_b32 s13, 0
	v_lshlrev_b32_e32 v1, 2, v1
	v_lshlrev_b32_e32 v89, 2, v3
	v_lshl_add_u64 v[72:73], v[70:71], 0, s[14:15]
	v_lshl_add_u64 v[74:75], v[70:71], 0, s[16:17]
	v_lshl_add_u64 v[76:77], v[70:71], 0, s[18:19]
	v_lshl_add_u64 v[78:79], v[70:71], 0, s[20:21]
	v_lshl_add_u64 v[80:81], v[70:71], 0, s[22:23]
	v_lshl_add_u64 v[82:83], v[70:71], 0, s[24:25]
	s_lshl_b64 s[26:27], s[8:9], 14
	s_lshl_b64 s[28:29], s[10:11], 14
	v_lshlrev_b32_e32 v66, 4, v2
	s_movk_i32 s33, 0x1000
	s_movk_i32 s36, 0x2000
	s_movk_i32 s37, 0x3000
	v_mov_b32_e32 v90, 0x358637bd
	s_mov_b32 s38, 0xf800000
	v_mov_b32_e32 v91, 0x260
	s_branch .LBB0_16
